# early-L1-invalidate-at-barrier-arrival
# speedup vs baseline: 1.0106x; 1.0106x over previous
; __device__ __forceinline__ unsigned xb_ld(unsigned* p)              { return __hip_atomic_load(p, __ATOMIC_RELAXED, __HIP_MEMORY_SCOPE_AGENT); }
; __device__ __forceinline__ unsigned xb_add(unsigned* p, unsigned v) { return __hip_atomic_fetch_add(p, v, __ATOMIC_RELAXED, __HIP_MEMORY_SCOPE_AGENT); }
; #define XB_SPIN(cond, bar) do { unsigned _sp = 0; while (cond) { __builtin_amdgcn_s_sleep(1); \
;     if ((++_sp & 255u) == 0u) { if (xb_ld(&(bar)[XB_TMO])) break; if (_sp > XB_SPIN_CAP) { atomicAdd(&(bar)[XB_TMO], 1u); break; } } } } while (0)
; __device__ __forceinline__ void xcd_barrier(const XcdBarrier& b) {
;     ...
;         const unsigned old = xb_add(&bar[XB_XSUB(b.x)], 1u);
;         const unsigned gen = old / nloc;
;         if (old + 1u == (gen + 1u) * nloc) {
;             __builtin_amdgcn_fence(__ATOMIC_RELEASE, "agent");
;             asm volatile("s_waitcnt vmcnt(0)" ::: "memory");
;             const unsigned og = xb_add(&bar[XB_TOP], 1u);
;             const unsigned tg = og / nx;
;             if (og + 1u == (tg + 1u) * nx) xb_add(&bar[XB_TOPGEN], 1u);
;             else XB_SPIN(xb_ld(&bar[XB_TOPGEN]) == tg, bar);
;             __builtin_amdgcn_fence(__ATOMIC_ACQUIRE, "agent");
;             xb_add(&bar[XB_XGEN(b.x)], 1u);
;             asm volatile("s_waitcnt vmcnt(0)" ::: "memory");
;         } else {
;             XB_SPIN(xb_ld(&bar[XB_XGEN(b.x)]) == gen, bar);
;             __builtin_amdgcn_fence(__ATOMIC_ACQUIRE, "agent");
;             asm volatile("s_waitcnt vmcnt(0)" ::: "memory");
;         }
.LBB0_49:
	s_or_b64 exec, exec, s[6:7]
	buffer_inv sc1
	v_cvt_f32_u32_e32 v4, v2
	s_waitcnt vmcnt(1)
	v_readfirstlane_b32 s4, v3
	v_sub_u32_e32 v3, 0, v2
	v_rcp_iflag_f32_e32 v4, v4
	v_add_u32_e32 v5, s4, v1
	v_mul_f32_e32 v4, 0x4f7ffffe, v4
	v_cvt_u32_f32_e32 v4, v4
	v_mul_lo_u32 v1, v3, v4
	v_mul_hi_u32 v1, v4, v1
	v_add_u32_e32 v1, v4, v1
	v_mul_hi_u32 v1, v5, v1
	v_mul_lo_u32 v3, v1, v2
	v_sub_u32_e32 v3, v5, v3
	v_add_u32_e32 v4, 1, v1
	v_cmp_ge_u32_e32 vcc, v3, v2
	s_nop 1
	v_cndmask_b32_e32 v1, v1, v4, vcc
	v_sub_u32_e32 v4, v3, v2
	v_cndmask_b32_e32 v3, v3, v4, vcc
	v_add_u32_e32 v4, 1, v1
	v_cmp_ge_u32_e32 vcc, v3, v2
	v_add_u32_e32 v3, 1, v5
	s_nop 0
	v_cndmask_b32_e32 v1, v1, v4, vcc
	v_mul_lo_u32 v4, v2, v1
	v_add_u32_e32 v2, v4, v2
	v_cmp_ne_u32_e32 vcc, v3, v2
	s_and_saveexec_b64 s[4:5], vcc
	s_xor_b64 s[4:5], exec, s[4:5]
	s_cbranch_execz .LBB0_63
	s_waitcnt lgkmcnt(0)
	v_mov_b32_e32 v0, 0x2000
	global_load_dword v0, v0, s[2:3] offset:1024 sc1
	s_add_u32 s8, s2, 0x2400
	s_addc_u32 s9, s3, 0
	s_waitcnt vmcnt(0)
	v_cmp_eq_u32_e32 vcc, v0, v1
	s_and_saveexec_b64 s[6:7], vcc
	s_cbranch_execz .LBB0_62
	s_mov_b32 s20, 1
	s_mov_b64 s[10:11], 0
	v_mov_b32_e32 v0, 0
	s_branch .LBB0_53

; __device__ __forceinline__ unsigned xb_ld(unsigned* p)              { return __hip_atomic_load(p, __ATOMIC_RELAXED, __HIP_MEMORY_SCOPE_AGENT); }
; #define XB_SPIN(cond, bar) do { unsigned _sp = 0; while (cond) { __builtin_amdgcn_s_sleep(1); \
;     if ((++_sp & 255u) == 0u) { if (xb_ld(&(bar)[XB_TMO])) break; if (_sp > XB_SPIN_CAP) { atomicAdd(&(bar)[XB_TMO], 1u); break; } } } } while (0)
; __device__ __forceinline__ void xcd_barrier(const XcdBarrier& b) {
;     ...
;             XB_SPIN(xb_ld(&bar[XB_XGEN(b.x)]) == gen, bar);
;             __builtin_amdgcn_fence(__ATOMIC_ACQUIRE, "agent");
;             asm volatile("s_waitcnt vmcnt(0)" ::: "memory");
.LBB0_62:
	s_or_b64 exec, exec, s[6:7]
	s_waitcnt vmcnt(0)
	s_waitcnt vmcnt(0)

; __device__ __forceinline__ unsigned xb_ld(unsigned* p)              { return __hip_atomic_load(p, __ATOMIC_RELAXED, __HIP_MEMORY_SCOPE_AGENT); }
; __device__ __forceinline__ unsigned xb_add(unsigned* p, unsigned v) { return __hip_atomic_fetch_add(p, v, __ATOMIC_RELAXED, __HIP_MEMORY_SCOPE_AGENT); }
; #define XB_SPIN(cond, bar) do { unsigned _sp = 0; while (cond) { __builtin_amdgcn_s_sleep(1); \
;     if ((++_sp & 255u) == 0u) { if (xb_ld(&(bar)[XB_TMO])) break; if (_sp > XB_SPIN_CAP) { atomicAdd(&(bar)[XB_TMO], 1u); break; } } } } while (0)
; __device__ __forceinline__ void xcd_barrier(const XcdBarrier& b) {
;     ...
;             if (og + 1u == (tg + 1u) * nx) xb_add(&bar[XB_TOPGEN], 1u);
;             else XB_SPIN(xb_ld(&bar[XB_TOPGEN]) == tg, bar);
;             __builtin_amdgcn_fence(__ATOMIC_ACQUIRE, "agent");
;             xb_add(&bar[XB_XGEN(b.x)], 1u);
.LBB0_80:
	s_or_b64 exec, exec, s[4:5]
	s_mov_b64 s[4:5], exec
	v_mbcnt_lo_u32_b32 v0, s4, 0
	v_mbcnt_hi_u32_b32 v0, s5, v0
	v_cmp_eq_u32_e32 vcc, 0, v0
	s_waitcnt vmcnt(0)
	s_and_saveexec_b64 s[6:7], vcc
	s_cbranch_execz .LBB0_82
	s_bcnt1_i32_b64 s4, s[4:5]
	v_mov_b32_e32 v0, 0x2000
	v_mov_b32_e32 v1, s4
	global_atomic_add v0, v1, s[2:3] offset:1024

; __device__ __forceinline__ unsigned xb_ld(unsigned* p)              { return __hip_atomic_load(p, __ATOMIC_RELAXED, __HIP_MEMORY_SCOPE_AGENT); }
; __device__ __forceinline__ unsigned xb_add(unsigned* p, unsigned v) { return __hip_atomic_fetch_add(p, v, __ATOMIC_RELAXED, __HIP_MEMORY_SCOPE_AGENT); }
; #define XB_SPIN(cond, bar) do { unsigned _sp = 0; while (cond) { __builtin_amdgcn_s_sleep(1); \
;     if ((++_sp & 255u) == 0u) { if (xb_ld(&(bar)[XB_TMO])) break; if (_sp > XB_SPIN_CAP) { atomicAdd(&(bar)[XB_TMO], 1u); break; } } } } while (0)
; __device__ __forceinline__ void xcd_barrier(const XcdBarrier& b) {
;     ...
;         const unsigned old = xb_add(&bar[XB_XSUB(b.x)], 1u);
;         const unsigned gen = old / nloc;
;         if (old + 1u == (gen + 1u) * nloc) {
;             __builtin_amdgcn_fence(__ATOMIC_RELEASE, "agent");
;             asm volatile("s_waitcnt vmcnt(0)" ::: "memory");
;             const unsigned og = xb_add(&bar[XB_TOP], 1u);
;             const unsigned tg = og / nx;
;             if (og + 1u == (tg + 1u) * nx) xb_add(&bar[XB_TOPGEN], 1u);
;             else XB_SPIN(xb_ld(&bar[XB_TOPGEN]) == tg, bar);
;             __builtin_amdgcn_fence(__ATOMIC_ACQUIRE, "agent");
;             xb_add(&bar[XB_XGEN(b.x)], 1u);
;             asm volatile("s_waitcnt vmcnt(0)" ::: "memory");
;         } else {
;             XB_SPIN(xb_ld(&bar[XB_XGEN(b.x)]) == gen, bar);
;             __builtin_amdgcn_fence(__ATOMIC_ACQUIRE, "agent");
;             asm volatile("s_waitcnt vmcnt(0)" ::: "memory");
;         }
.LBB0_624:
	s_or_b64 exec, exec, s[8:9]
	buffer_inv sc1
	v_cvt_f32_u32_e32 v4, v2
	s_waitcnt vmcnt(1)
	v_readfirstlane_b32 s6, v3
	v_sub_u32_e32 v3, 0, v2
	v_rcp_iflag_f32_e32 v4, v4
	v_add_u32_e32 v5, s6, v1
	v_mul_f32_e32 v4, 0x4f7ffffe, v4
	v_cvt_u32_f32_e32 v4, v4
	v_mul_lo_u32 v1, v3, v4
	v_mul_hi_u32 v1, v4, v1
	v_add_u32_e32 v1, v4, v1
	v_mul_hi_u32 v1, v5, v1
	v_mul_lo_u32 v3, v1, v2
	v_sub_u32_e32 v3, v5, v3
	v_add_u32_e32 v4, 1, v1
	v_cmp_ge_u32_e32 vcc, v3, v2
	s_nop 1
	v_cndmask_b32_e32 v1, v1, v4, vcc
	v_sub_u32_e32 v4, v3, v2
	v_cndmask_b32_e32 v3, v3, v4, vcc
	v_add_u32_e32 v4, 1, v1
	v_cmp_ge_u32_e32 vcc, v3, v2
	v_add_u32_e32 v3, 1, v5
	s_nop 0
	v_cndmask_b32_e32 v1, v1, v4, vcc
	v_mul_lo_u32 v4, v2, v1
	v_add_u32_e32 v2, v4, v2
	v_cmp_ne_u32_e32 vcc, v3, v2
	s_and_saveexec_b64 s[6:7], vcc
	s_xor_b64 s[6:7], exec, s[6:7]
	s_cbranch_execz .LBB0_638
	s_waitcnt lgkmcnt(0)
	v_mov_b32_e32 v0, 0x2000
	global_load_dword v0, v0, s[2:3] offset:1024 sc1
	s_add_u32 s10, s2, 0x2400
	s_addc_u32 s11, s3, 0
	s_waitcnt vmcnt(0)
	v_cmp_eq_u32_e32 vcc, v0, v1
	s_and_saveexec_b64 s[8:9], vcc
	s_cbranch_execz .LBB0_637
	s_mov_b32 s22, 1
	s_mov_b64 s[12:13], 0
	v_mov_b32_e32 v0, 0
	s_branch .LBB0_628

; __device__ __forceinline__ unsigned xb_ld(unsigned* p)              { return __hip_atomic_load(p, __ATOMIC_RELAXED, __HIP_MEMORY_SCOPE_AGENT); }
; #define XB_SPIN(cond, bar) do { unsigned _sp = 0; while (cond) { __builtin_amdgcn_s_sleep(1); \
;     if ((++_sp & 255u) == 0u) { if (xb_ld(&(bar)[XB_TMO])) break; if (_sp > XB_SPIN_CAP) { atomicAdd(&(bar)[XB_TMO], 1u); break; } } } } while (0)
; __device__ __forceinline__ void xcd_barrier(const XcdBarrier& b) {
;     ...
;             XB_SPIN(xb_ld(&bar[XB_XGEN(b.x)]) == gen, bar);
;             __builtin_amdgcn_fence(__ATOMIC_ACQUIRE, "agent");
;             asm volatile("s_waitcnt vmcnt(0)" ::: "memory");
.LBB0_637:
	s_or_b64 exec, exec, s[8:9]
	s_waitcnt vmcnt(0)
	s_waitcnt vmcnt(0)

; __device__ __forceinline__ unsigned xb_ld(unsigned* p)              { return __hip_atomic_load(p, __ATOMIC_RELAXED, __HIP_MEMORY_SCOPE_AGENT); }
; __device__ __forceinline__ unsigned xb_add(unsigned* p, unsigned v) { return __hip_atomic_fetch_add(p, v, __ATOMIC_RELAXED, __HIP_MEMORY_SCOPE_AGENT); }
; #define XB_SPIN(cond, bar) do { unsigned _sp = 0; while (cond) { __builtin_amdgcn_s_sleep(1); \
;     if ((++_sp & 255u) == 0u) { if (xb_ld(&(bar)[XB_TMO])) break; if (_sp > XB_SPIN_CAP) { atomicAdd(&(bar)[XB_TMO], 1u); break; } } } } while (0)
; __device__ __forceinline__ void xcd_barrier(const XcdBarrier& b) {
;     ...
;             if (og + 1u == (tg + 1u) * nx) xb_add(&bar[XB_TOPGEN], 1u);
;             else XB_SPIN(xb_ld(&bar[XB_TOPGEN]) == tg, bar);
;             __builtin_amdgcn_fence(__ATOMIC_ACQUIRE, "agent");
;             xb_add(&bar[XB_XGEN(b.x)], 1u);
.LBB0_655:
	s_or_b64 exec, exec, s[6:7]
	s_mov_b64 s[6:7], exec
	v_mbcnt_lo_u32_b32 v0, s6, 0
	v_mbcnt_hi_u32_b32 v0, s7, v0
	v_cmp_eq_u32_e32 vcc, 0, v0
	s_waitcnt vmcnt(0)
	s_and_saveexec_b64 s[8:9], vcc
	s_cbranch_execz .LBB0_657
	s_bcnt1_i32_b64 s6, s[6:7]
	v_mov_b32_e32 v0, 0x2000
	v_mov_b32_e32 v1, s6
	global_atomic_add v0, v1, s[2:3] offset:1024
